# attention compute: waves 4-7 (second wave of each SIMD) run at s_setprio 3 so the pair leaves lockstep; reset before the end-of-item barrier
# speedup vs baseline: 1.0004x; 1.0004x over previous
.LBB0_347:
	v_cndmask_b32_e64 v72, v48, v212, s[2:3]
	v_cndmask_b32_e64 v167, v72, v48, s[4:5]
	v_max3_f32 v48, v98, s64, v105
	v_max3_f32 v48, v48, v104, v103
	v_max3_f32 v48, v48, v102, v101
	v_max3_f32 v48, v48, v100, v99
	v_max3_f32 v48, v48, v71, v70
	v_max3_f32 v48, v48, v69, v68
	v_max3_f32 v48, v48, v67, v66
	v_max3_f32 v48, v48, v65, v64
	v_max3_f32 v48, v48, v32, v33
	v_max3_f32 v48, v48, v34, v35
	v_max3_f32 v48, v48, v36, v37
	v_max3_f32 v48, v48, v38, v39
	v_max3_f32 v48, v48, v40, v41
	v_max3_f32 v48, v48, v42, v43
	v_max3_f32 v48, v48, v44, v45
	v_max3_f32 v48, v48, v46, v47
	v_max3_f32 v48, v48, v16, v17
	v_max3_f32 v48, v48, v18, v19
	v_max3_f32 v48, v48, v20, v21
	v_max3_f32 v48, v48, v22, v23
	v_max3_f32 v48, v48, v24, v25
	v_max3_f32 v48, v48, v26, v27
	v_max3_f32 v48, v48, v28, v29
	v_max3_f32 v48, v48, v30, v31
	v_max3_f32 v48, v48, v0, v1
	v_max3_f32 v48, v48, v2, v3
	v_max3_f32 v48, v48, v4, v5
	v_max3_f32 v48, v48, v6, v7
	v_max3_f32 v48, v48, v8, v9
	v_max3_f32 v48, v48, v10, v11
	v_max3_f32 v48, v48, v12, v13
	v_cndmask_b32_e64 v166, v212, v49, s[4:5]
	v_max3_f32 v48, v48, v14, v15
	v_cndmask_b32_e64 v168, v50, v212, s[6:7]
	v_cndmask_b32_e64 v169, v51, v212, s[8:9]
	v_max3_f32 v48, v48, v167, v166
	v_cndmask_b32_e64 v170, v52, v212, s[10:11]
	v_cndmask_b32_e64 v171, v53, v212, s[12:13]
	v_max3_f32 v48, v48, v168, v169
	v_cndmask_b32_e64 v172, v54, v212, s[14:15]
	v_cndmask_b32_e64 v173, v55, v212, s[16:17]
	v_max3_f32 v48, v48, v170, v171
	v_cndmask_b32_e64 v174, v56, v212, s[18:19]
	v_cndmask_b32_e64 v175, v57, v212, s[20:21]
	v_max3_f32 v48, v48, v172, v173
	v_cndmask_b32_e64 v176, v58, v212, s[22:23]
	v_cndmask_b32_e64 v177, v59, v212, s[24:25]
	v_max3_f32 v48, v48, v174, v175
	v_cndmask_b32_e64 v178, v60, v212, s[26:27]
	v_cndmask_b32_e64 v179, v61, v212, s[28:29]
	v_max3_f32 v48, v48, v176, v177
	v_cndmask_b32_e64 v180, v62, v212, s[30:31]
	v_cndmask_b32_e64 v181, v63, v212, s[34:35]
	v_max3_f32 v48, v48, v178, v179
	v_max3_f32 v48, v48, v180, v181
	ds_bpermute_b32 v49, v188, v48
	v_or_b32_e32 v153, s89, v118
	v_readlane_b32 s0, v255, 16
	s_add_i32 s96, s96, s1
	s_add_i32 s90, s90, s0
	s_waitcnt lgkmcnt(0)
	v_max3_f32 v213, v48, v49, v96
	v_sub_f32_e32 v50, v104, v213
	v_exp_f32_e32 v154, v50
	v_sub_f32_e32 v50, v103, v213
	v_exp_f32_e32 v155, v50
	v_sub_f32_e32 v50, v102, v213
	v_exp_f32_e32 v160, v50
	v_sub_f32_e32 v50, v101, v213
	v_exp_f32_e32 v161, v50
	v_sub_f32_e32 v50, v100, v213
	v_sub_f32_e32 v48, v98, v213
	v_exp_f32_e32 v164, v50
	v_sub_f32_e32 v50, v99, v213
	v_exp_f32_e32 v110, v48
	v_sub_f32_e32 v48, v105, v213
	v_exp_f32_e32 v165, v50
	v_sub_f32_e32 v50, v71, v213
	v_exp_f32_e32 v111, v48
	v_exp_f32_e32 v102, v50
	v_sub_f32_e32 v50, v70, v213
	v_exp_f32_e32 v103, v50
	v_sub_f32_e32 v50, v69, v213
	v_sub_f32_e32 v34, v34, v213
	v_exp_f32_e32 v112, v50
	v_sub_f32_e32 v50, v68, v213
	v_exp_f32_e32 v106, v34
	v_sub_f32_e32 v34, v35, v213
	v_exp_f32_e32 v113, v50
	v_sub_f32_e32 v50, v67, v213
	v_exp_f32_e32 v107, v34
	v_sub_f32_e32 v34, v36, v213
	v_pk_add_f32 v[48:49], v[110:111], 0 op_sel_hi:[1,0]
	v_exp_f32_e32 v156, v50
	v_sub_f32_e32 v50, v66, v213
	v_exp_f32_e32 v118, v34
	v_sub_f32_e32 v34, v37, v213
	v_pk_add_f32 v[48:49], v[154:155], v[48:49]
	v_exp_f32_e32 v157, v50
	v_sub_f32_e32 v50, v65, v213
	v_exp_f32_e32 v119, v34
	v_sub_f32_e32 v34, v38, v213
	v_pk_add_f32 v[48:49], v[160:161], v[48:49]
	v_exp_f32_e32 v162, v50
	v_sub_f32_e32 v50, v64, v213
	v_sub_f32_e32 v32, v32, v213
	v_exp_f32_e32 v158, v34
	v_sub_f32_e32 v34, v39, v213
	v_pk_add_f32 v[48:49], v[164:165], v[48:49]
	v_exp_f32_e32 v163, v50
	v_exp_f32_e32 v78, v32
	v_sub_f32_e32 v32, v33, v213
	v_exp_f32_e32 v159, v34
	v_sub_f32_e32 v34, v40, v213
	v_pk_add_f32 v[48:49], v[102:103], v[48:49]
	v_exp_f32_e32 v79, v32
	v_exp_f32_e32 v68, v34
	v_sub_f32_e32 v34, v41, v213
	v_pk_add_f32 v[48:49], v[112:113], v[48:49]
	v_exp_f32_e32 v69, v34
	v_sub_f32_e32 v34, v42, v213
	v_sub_f32_e32 v18, v18, v213
	v_sub_f32_e32 v2, v2, v213
	v_pk_add_f32 v[48:49], v[156:157], v[48:49]
	v_exp_f32_e32 v76, v34
	v_sub_f32_e32 v34, v43, v213
	v_exp_f32_e32 v72, v18
	v_sub_f32_e32 v18, v19, v213
	v_exp_f32_e32 v60, v2
	v_sub_f32_e32 v2, v3, v213
	v_pk_add_f32 v[48:49], v[162:163], v[48:49]
	v_exp_f32_e32 v77, v34
	v_sub_f32_e32 v34, v44, v213
	v_exp_f32_e32 v73, v18
	v_sub_f32_e32 v18, v20, v213
	v_exp_f32_e32 v61, v2
	v_sub_f32_e32 v2, v4, v213
	v_pk_add_f32 v[32:33], v[78:79], v[48:49]
	v_exp_f32_e32 v104, v34
	v_sub_f32_e32 v34, v45, v213
	v_exp_f32_e32 v100, v18
	v_sub_f32_e32 v18, v21, v213
	v_exp_f32_e32 v66, v2
	v_sub_f32_e32 v2, v5, v213
	v_pk_add_f32 v[32:33], v[106:107], v[32:33]
	v_exp_f32_e32 v105, v34
	v_sub_f32_e32 v34, v46, v213
	v_exp_f32_e32 v101, v18
	v_sub_f32_e32 v18, v22, v213
	v_exp_f32_e32 v67, v2
	v_sub_f32_e32 v2, v6, v213
	v_pk_add_f32 v[32:33], v[118:119], v[32:33]
	v_exp_f32_e32 v114, v34
	v_sub_f32_e32 v34, v47, v213
	v_sub_f32_e32 v16, v16, v213
	v_exp_f32_e32 v108, v18
	v_sub_f32_e32 v18, v23, v213
	v_exp_f32_e32 v74, v2
	v_sub_f32_e32 v2, v7, v213
	v_pk_add_f32 v[32:33], v[158:159], v[32:33]
	v_exp_f32_e32 v115, v34
	v_exp_f32_e32 v64, v16
	v_sub_f32_e32 v16, v17, v213
	v_exp_f32_e32 v109, v18
	v_sub_f32_e32 v18, v24, v213
	v_exp_f32_e32 v75, v2
	v_sub_f32_e32 v2, v8, v213
	v_pk_add_f32 v[32:33], v[68:69], v[32:33]
	v_exp_f32_e32 v65, v16
	v_exp_f32_e32 v58, v18
	v_sub_f32_e32 v18, v25, v213
	v_exp_f32_e32 v48, v2
	v_sub_f32_e32 v2, v9, v213
	v_pk_add_f32 v[32:33], v[76:77], v[32:33]
	v_exp_f32_e32 v59, v18
	v_sub_f32_e32 v18, v26, v213
	v_exp_f32_e32 v49, v2
	v_sub_f32_e32 v2, v10, v213
	v_pk_add_f32 v[32:33], v[104:105], v[32:33]
	v_exp_f32_e32 v62, v18
	v_sub_f32_e32 v18, v27, v213
	v_exp_f32_e32 v50, v2
	v_sub_f32_e32 v2, v11, v213
	v_pk_add_f32 v[32:33], v[114:115], v[32:33]
	v_exp_f32_e32 v63, v18
	v_sub_f32_e32 v18, v28, v213
	v_exp_f32_e32 v51, v2
	v_sub_f32_e32 v2, v12, v213
	v_pk_add_f32 v[16:17], v[64:65], v[32:33]
	v_exp_f32_e32 v70, v18
	v_sub_f32_e32 v18, v29, v213
	v_exp_f32_e32 v52, v2
	v_sub_f32_e32 v2, v13, v213
	v_pk_add_f32 v[16:17], v[72:73], v[16:17]
	v_exp_f32_e32 v71, v18
	v_sub_f32_e32 v18, v30, v213
	v_exp_f32_e32 v53, v2
	v_sub_f32_e32 v2, v14, v213
	v_pk_add_f32 v[16:17], v[100:101], v[16:17]
	v_exp_f32_e32 v98, v18
	v_sub_f32_e32 v18, v31, v213
	v_sub_f32_e32 v0, v0, v213
	v_exp_f32_e32 v54, v2
	v_sub_f32_e32 v2, v15, v213
	v_pk_add_f32 v[16:17], v[108:109], v[16:17]
	v_exp_f32_e32 v99, v18
	v_exp_f32_e32 v56, v0
	v_sub_f32_e32 v0, v1, v213
	v_exp_f32_e32 v55, v2
	v_sub_f32_e32 v2, v167, v213
	v_pk_add_f32 v[16:17], v[58:59], v[16:17]
	v_exp_f32_e32 v57, v0
	v_exp_f32_e32 v40, v2
	v_sub_f32_e32 v2, v166, v213
	v_pk_add_f32 v[16:17], v[62:63], v[16:17]
	v_exp_f32_e32 v41, v2
	v_sub_f32_e32 v2, v168, v213
	v_pk_add_f32 v[16:17], v[70:71], v[16:17]
	v_exp_f32_e32 v42, v2
	v_sub_f32_e32 v2, v169, v213
	v_pk_add_f32 v[16:17], v[98:99], v[16:17]
	v_exp_f32_e32 v43, v2
	v_sub_f32_e32 v2, v170, v213
	v_pk_add_f32 v[0:1], v[56:57], v[16:17]
	v_exp_f32_e32 v44, v2
	v_sub_f32_e32 v2, v171, v213
	v_pk_add_f32 v[0:1], v[60:61], v[0:1]
	v_exp_f32_e32 v45, v2
	v_sub_f32_e32 v2, v172, v213
	v_pk_add_f32 v[0:1], v[66:67], v[0:1]
	v_exp_f32_e32 v46, v2
	v_sub_f32_e32 v2, v173, v213
	v_pk_add_f32 v[0:1], v[74:75], v[0:1]
	v_exp_f32_e32 v47, v2
	v_sub_f32_e32 v2, v174, v213
	v_pk_add_f32 v[0:1], v[48:49], v[0:1]
	v_exp_f32_e32 v32, v2
	v_sub_f32_e32 v2, v175, v213
	v_pk_add_f32 v[0:1], v[50:51], v[0:1]
	v_exp_f32_e32 v33, v2
	v_sub_f32_e32 v2, v176, v213
	v_pk_add_f32 v[0:1], v[52:53], v[0:1]
	v_exp_f32_e32 v34, v2
	v_sub_f32_e32 v2, v177, v213
	v_pk_add_f32 v[0:1], v[54:55], v[0:1]
	v_exp_f32_e32 v35, v2
	v_sub_f32_e32 v2, v178, v213
	v_pk_add_f32 v[0:1], v[40:41], v[0:1]
	v_exp_f32_e32 v36, v2
	v_sub_f32_e32 v2, v179, v213
	v_pk_add_f32 v[0:1], v[42:43], v[0:1]
	v_exp_f32_e32 v37, v2
	v_sub_f32_e32 v2, v180, v213
	v_pk_add_f32 v[0:1], v[44:45], v[0:1]
	v_exp_f32_e32 v38, v2
	v_sub_f32_e32 v2, v181, v213
	v_pk_add_f32 v[0:1], v[46:47], v[0:1]
	v_exp_f32_e32 v39, v2
	v_pk_add_f32 v[0:1], v[32:33], v[0:1]
	v_cvt_pk_bf16_f32 v16, v110, v111
	v_cvt_pk_bf16_f32 v17, v154, v155
	v_add_u32_e32 v154, 0x9000, v207
	v_pk_add_f32 v[0:1], v[34:35], v[0:1]
	v_cvt_pk_bf16_f32 v18, v160, v161
	v_cvt_pk_bf16_f32 v19, v164, v165
	v_add_u32_e32 v160, 0xd000, v207
	v_pk_add_f32 v[0:1], v[36:37], v[0:1]
	ds_read2_b64 v[20:23], v160 offset0:32 offset1:34
	v_pk_add_f32 v[0:1], v[38:39], v[0:1]
	s_nop 0
	v_add_f32_e32 v0, v0, v1
	ds_bpermute_b32 v1, v188, v0
	s_waitcnt lgkmcnt(0)
	v_add_f32_e32 v0, v0, v1
	v_sub_f32_e32 v1, v96, v213
	v_exp_f32_e32 v1, v1
	s_nop 0
	v_add_f32_e32 v96, v1, v0
	ds_read2_b64 v[0:3], v154 offset1:2
	v_cvt_pk_bf16_f32 v110, v102, v103
	v_cvt_pk_bf16_f32 v111, v112, v113
	v_cvt_pk_bf16_f32 v112, v156, v157
	v_cvt_pk_bf16_f32 v113, v162, v163
	ds_read2_b64 v[154:157], v154 offset0:4 offset1:6
	s_waitcnt lgkmcnt(1)
	v_mfma_f32_32x32x16_bf16 v[0:15], v[0:3], v[16:19], 0
	s_waitcnt lgkmcnt(0)
	v_mfma_f32_32x32x16_bf16 v[0:15], v[154:157], v[110:113], v[0:15]
	ds_read2_b64 v[154:157], v160 offset0:36 offset1:38
	v_mfma_f32_32x32x16_bf16 v[16:31], v[20:23], v[16:19], 0
	s_waitcnt lgkmcnt(0)
	v_mfma_f32_32x32x16_bf16 v[16:31], v[154:157], v[110:113], v[16:31]
	v_cvt_pk_bf16_f32 v110, v78, v79
	v_add_u32_e32 v78, 0x9000, v208
	v_cvt_pk_bf16_f32 v111, v106, v107
	v_cvt_pk_bf16_f32 v112, v118, v119
	v_cvt_pk_bf16_f32 v113, v158, v159
	ds_read2_b64 v[154:157], v78 offset1:2
	v_add_u32_e32 v106, 0xd000, v208
	s_waitcnt lgkmcnt(0)
	v_mfma_f32_32x32x16_bf16 v[0:15], v[154:157], v[110:113], v[0:15]
	ds_read2_b64 v[154:157], v106 offset0:32 offset1:34
	v_cvt_pk_bf16_f32 v102, v68, v69
	v_cvt_pk_bf16_f32 v103, v76, v77
	v_cvt_pk_bf16_f32 v104, v104, v105
	v_cvt_pk_bf16_f32 v105, v114, v115
	ds_read2_b64 v[76:79], v78 offset0:4 offset1:6
	s_waitcnt lgkmcnt(0)
	v_mfma_f32_32x32x16_bf16 v[0:15], v[76:79], v[102:105], v[0:15]
	ds_read2_b64 v[76:79], v106 offset0:36 offset1:38
	v_mfma_f32_32x32x16_bf16 v[16:31], v[154:157], v[110:113], v[16:31]
	s_waitcnt lgkmcnt(0)
	v_mfma_f32_32x32x16_bf16 v[16:31], v[76:79], v[102:105], v[16:31]
	v_cvt_pk_bf16_f32 v76, v64, v65
	v_add_u32_e32 v64, 0x9000, v209
	v_cvt_pk_bf16_f32 v77, v72, v73
	v_cvt_pk_bf16_f32 v78, v100, v101
	v_cvt_pk_bf16_f32 v79, v108, v109
	ds_read2_b64 v[100:103], v64 offset1:2
	v_add_u32_e32 v72, 0xd000, v209
	s_waitcnt lgkmcnt(0)
	v_mfma_f32_32x32x16_bf16 v[0:15], v[100:103], v[76:79], v[0:15]
	ds_read2_b64 v[100:103], v72 offset0:32 offset1:34
	v_cvt_pk_bf16_f32 v68, v58, v59
	v_cvt_pk_bf16_f32 v69, v62, v63
	v_cvt_pk_bf16_f32 v70, v70, v71
	v_cvt_pk_bf16_f32 v71, v98, v99
	ds_read2_b64 v[62:65], v64 offset0:4 offset1:6
	s_waitcnt lgkmcnt(0)
	v_mfma_f32_32x32x16_bf16 v[0:15], v[62:65], v[68:71], v[0:15]
	ds_read2_b64 v[62:65], v72 offset0:36 offset1:38
	v_cvt_pk_bf16_f32 v56, v56, v57
	v_cvt_pk_bf16_f32 v57, v60, v61
	v_cvt_pk_bf16_f32 v58, v66, v67
	v_cvt_pk_bf16_f32 v59, v74, v75
	v_mfma_f32_32x32x16_bf16 v[16:31], v[100:103], v[76:79], v[16:31]
	s_waitcnt lgkmcnt(0)
	v_mfma_f32_32x32x16_bf16 v[16:31], v[62:65], v[68:71], v[16:31]
	v_add_u32_e32 v64, 0x9000, v210
	ds_read2_b64 v[60:63], v64 offset1:2
	v_add_u32_e32 v65, 0xd000, v210
	s_waitcnt lgkmcnt(0)
	v_mfma_f32_32x32x16_bf16 v[0:15], v[60:63], v[56:59], v[0:15]
	ds_read2_b64 v[60:63], v65 offset0:32 offset1:34
	v_cvt_pk_bf16_f32 v48, v48, v49
	v_cvt_pk_bf16_f32 v49, v50, v51
	v_cvt_pk_bf16_f32 v50, v52, v53
	v_cvt_pk_bf16_f32 v51, v54, v55
	ds_read2_b64 v[52:55], v64 offset0:4 offset1:6
	s_waitcnt lgkmcnt(0)
	v_mfma_f32_32x32x16_bf16 v[0:15], v[52:55], v[48:51], v[0:15]
	ds_read2_b64 v[52:55], v65 offset0:36 offset1:38
	v_cvt_pk_bf16_f32 v40, v40, v41
	v_cvt_pk_bf16_f32 v41, v42, v43
	v_cvt_pk_bf16_f32 v42, v44, v45
	v_cvt_pk_bf16_f32 v43, v46, v47
	v_mfma_f32_32x32x16_bf16 v[16:31], v[60:63], v[56:59], v[16:31]
	s_waitcnt lgkmcnt(0)
	v_mfma_f32_32x32x16_bf16 v[16:31], v[52:55], v[48:51], v[16:31]
	v_add_u32_e32 v48, 0x9000, v211
	ds_read2_b64 v[44:47], v48 offset1:2
	v_add_u32_e32 v49, 0xd000, v211
	s_waitcnt lgkmcnt(0)
	v_mfma_f32_32x32x16_bf16 v[0:15], v[44:47], v[40:43], v[0:15]
	ds_read2_b64 v[44:47], v49 offset0:32 offset1:34
	v_cvt_pk_bf16_f32 v32, v32, v33
	v_cvt_pk_bf16_f32 v33, v34, v35
	v_cvt_pk_bf16_f32 v34, v36, v37
	v_cvt_pk_bf16_f32 v35, v38, v39
	ds_read2_b64 v[36:39], v48 offset0:4 offset1:6
	s_waitcnt lgkmcnt(0)
	v_mfma_f32_32x32x16_bf16 v[0:15], v[36:39], v[32:35], v[0:15]
	ds_read2_b64 v[36:39], v49 offset0:36 offset1:38
	v_mfma_f32_32x32x16_bf16 v[16:31], v[44:47], v[40:43], v[16:31]
	s_waitcnt lgkmcnt(0)
	v_mfma_f32_32x32x16_bf16 v[16:31], v[36:39], v[32:35], v[16:31]
	v_div_scale_f32 v32, s[68:69], v96, v96, 1.0
	v_rcp_f32_e32 v33, v32
	s_nop 0
	v_fma_f32 v34, -v32, v33, 1.0
	v_fmac_f32_e32 v33, v34, v33
	v_div_scale_f32 v34, vcc, 1.0, v96, 1.0
	v_mul_f32_e32 v35, v34, v33
	v_fma_f32 v36, -v32, v35, v34
	v_fmac_f32_e32 v35, v36, v33
	v_fma_f32 v32, -v32, v35, v34
	v_div_fmas_f32 v32, v32, v33, v35
	v_div_fixup_f32 v34, v32, v96, 1.0
	v_mul_f32_e32 v0, v0, v34
	v_mul_f32_e32 v1, v1, v34
	v_cvt_pk_bf16_f32 v0, v0, v1
	v_mul_f32_e32 v1, v2, v34
	v_mad_i64_i32 v[32:33], s[68:69], v153, s65, v[116:117]
	v_and_b32_e32 v36, 63, v251
	v_and_b32_e32 v35, 31, v251
	v_lshrrev_b32_e32 v37, 5, v36
	v_lshlrev_b32_e32 v37, 3, v37
	s_movk_i32 s58, 0x90
	v_mad_u32_u24 v35, v35, s58, v37
	s_movk_i32 s59, 0x1200
	v_mad_u32_u24 v35, v254, s59, v35
	v_add_u32_e32 v35, 0x12000, v35
	v_lshrrev_b32_e32 v37, 3, v36
	v_and_b32_e32 v40, 7, v36
	v_lshlrev_b32_e32 v40, 4, v40
	v_mad_u32_u24 v36, v37, s58, v40
	v_mad_u32_u24 v36, v254, s59, v36
	v_add_u32_e32 v36, 0x12000, v36
	s_movk_i32 s58, 0xc00
	v_mad_u32_u24 v37, v37, s58, v40
	v_readfirstlane_b32 s56, v32
	v_readfirstlane_b32 s57, v33
	v_mul_f32_e32 v2, v3, v34
	v_cvt_pk_bf16_f32 v1, v1, v2
	ds_write_b64 v35, v[0:1]
	v_mul_f32_e32 v0, v4, v34
	v_mul_f32_e32 v1, v5, v34
	v_cvt_pk_bf16_f32 v0, v0, v1
	v_mul_f32_e32 v1, v6, v34
	v_mul_f32_e32 v2, v7, v34
	v_cvt_pk_bf16_f32 v1, v1, v2
	ds_write_b64 v35, v[0:1] offset:16
	v_mul_f32_e32 v0, v8, v34
	v_mul_f32_e32 v1, v9, v34
	v_cvt_pk_bf16_f32 v0, v0, v1
	v_mul_f32_e32 v1, v10, v34
	v_mul_f32_e32 v2, v11, v34
	v_cvt_pk_bf16_f32 v1, v1, v2
	ds_write_b64 v35, v[0:1] offset:32
	v_mul_f32_e32 v0, v12, v34
	v_mul_f32_e32 v1, v13, v34
	v_cvt_pk_bf16_f32 v0, v0, v1
	v_mul_f32_e32 v1, v14, v34
	v_mul_f32_e32 v2, v15, v34
	v_cvt_pk_bf16_f32 v1, v1, v2
	ds_write_b64 v35, v[0:1] offset:48
	v_mul_f32_e32 v0, v16, v34
	v_mul_f32_e32 v1, v17, v34
	v_cvt_pk_bf16_f32 v0, v0, v1
	v_mul_f32_e32 v1, v18, v34
	v_mul_f32_e32 v2, v19, v34
	v_cvt_pk_bf16_f32 v1, v1, v2
	ds_write_b64 v35, v[0:1] offset:64
	v_mul_f32_e32 v0, v20, v34
	v_mul_f32_e32 v1, v21, v34
	v_cvt_pk_bf16_f32 v0, v0, v1
	v_mul_f32_e32 v1, v22, v34
	v_mul_f32_e32 v2, v23, v34
	v_cvt_pk_bf16_f32 v1, v1, v2
	ds_write_b64 v35, v[0:1] offset:80
	v_mul_f32_e32 v0, v24, v34
	v_mul_f32_e32 v1, v25, v34
	v_cvt_pk_bf16_f32 v0, v0, v1
	v_mul_f32_e32 v1, v26, v34
	v_mul_f32_e32 v2, v27, v34
	v_cvt_pk_bf16_f32 v1, v1, v2
	ds_write_b64 v35, v[0:1] offset:96
	v_mul_f32_e32 v0, v28, v34
	v_mul_f32_e32 v1, v29, v34
	v_cvt_pk_bf16_f32 v0, v0, v1
	v_mul_f32_e32 v1, v30, v34
	s_andn2_b64 vcc, exec, s[76:77]
	v_mul_f32_e32 v2, v31, v34
	v_cvt_pk_bf16_f32 v1, v1, v2
	ds_write_b64 v35, v[0:1] offset:112
	s_waitcnt lgkmcnt(0)
	ds_read_b128 v[0:3], v36
	ds_read_b128 v[4:7], v36 offset:1152
	ds_read_b128 v[8:11], v36 offset:2304
	ds_read_b128 v[12:15], v36 offset:3456
	s_waitcnt lgkmcnt(3)
	global_store_dwordx4 v37, v[0:3], s[56:57]
	s_add_u32 s56, s56, 0x6000
	s_addc_u32 s57, s57, 0
	s_waitcnt lgkmcnt(2)
	global_store_dwordx4 v37, v[4:7], s[56:57]
	s_add_u32 s56, s56, 0x6000
	s_addc_u32 s57, s57, 0
	s_waitcnt lgkmcnt(1)
	global_store_dwordx4 v37, v[8:11], s[56:57]
	s_add_u32 s56, s56, 0x6000
	s_addc_u32 s57, s57, 0
	s_waitcnt lgkmcnt(0)
	global_store_dwordx4 v37, v[12:15], s[56:57]
	s_nop 1
	s_setprio 0
	s_barrier
	s_cbranch_vccz .LBB0_359

.LBB0_354:
	v_readfirstlane_b32 s58, v254
	s_cmp_lt_u32 s58, 4
	s_cbranch_scc1 .Lattn_prio_skip
	s_setprio 3
